# stack3 + softmax cross-row max via v_permlane16/32_swap instead of ds_bpermute
# speedup vs baseline: 1.0089x; 1.0089x over previous
.LBB0_722:
	v_max3_f32 v0, v142, s63, v143
	v_max3_f32 v0, v0, v144, v145
	v_max3_f32 v0, v0, v138, v139
	v_max3_f32 v0, v0, v140, v141
	v_max3_f32 v0, v0, v118, v119
	v_max3_f32 v0, v0, v120, v121
	v_max3_f32 v0, v0, v114, v115
	v_max3_f32 v0, v0, v116, v117
	v_mov_b32_e32 v190, v0
	s_andn2_b64 vcc, exec, s[6:7]
	s_nop 0
	v_permlane16_swap_b32_e32 v0, v190
	v_max_f32_e32 v0, v0, v190
	v_mov_b32_e32 v190, v0
	s_nop 1
	v_permlane32_swap_b32_e32 v0, v190
	v_max3_f32 v239, v189, v0, v190
	v_sub_f32_e32 v138, v138, v239
	v_exp_f32_e32 v203, v138
	v_sub_f32_e32 v138, v139, v239
	v_exp_f32_e32 v201, v138
	v_sub_f32_e32 v138, v140, v239
	v_sub_f32_e32 v114, v114, v239
	v_exp_f32_e32 v199, v138
	v_sub_f32_e32 v138, v141, v239
	v_exp_f32_e32 v141, v114
	v_sub_f32_e32 v114, v115, v239
	v_exp_f32_e32 v139, v114
	v_sub_f32_e32 v114, v116, v239
	v_sub_f32_e32 v0, v189, v239
	v_sub_f32_e32 v143, v143, v239
	v_exp_f32_e32 v189, v114
	v_sub_f32_e32 v114, v117, v239
	v_exp_f32_e32 v209, v143
	v_exp_f32_e32 v143, v114
	v_max3_f32 v114, v134, s63, v135
	v_max3_f32 v114, v114, v136, v137
	v_max3_f32 v114, v114, v130, v131
	v_sub_f32_e32 v118, v118, v239
	v_max3_f32 v114, v114, v132, v133
	v_exp_f32_e32 v195, v118
	v_sub_f32_e32 v118, v119, v239
	v_max3_f32 v114, v114, v126, v127
	v_exp_f32_e32 v193, v118
	v_sub_f32_e32 v118, v120, v239
	v_max3_f32 v114, v114, v128, v129
	v_sub_f32_e32 v145, v145, v239
	v_exp_f32_e32 v191, v118
	v_sub_f32_e32 v118, v121, v239
	v_max3_f32 v114, v114, v122, v123
	v_exp_f32_e32 v205, v145
	v_exp_f32_e32 v145, v118
	v_max3_f32 v118, v114, v124, v125
	v_mov_b32_e32 v119, v118
	v_exp_f32_e32 v197, v138
	v_sub_f32_e32 v142, v142, v239
	v_exp_f32_e32 v211, v142
	v_sub_f32_e32 v144, v144, v239
	v_permlane16_swap_b32_e32 v118, v119
	v_max_f32_e32 v138, v118, v119
	v_mov_b32_e32 v140, v138
	v_exp_f32_e32 v0, v0
	v_exp_f32_e32 v207, v144
	v_cvt_pk_bf16_f32 v114, v211, v209
	v_cvt_pk_bf16_f32 v115, v207, v205
	v_permlane32_swap_b32_e32 v138, v140
	v_max3_f32 v240, v188, v138, v140
	v_sub_f32_e32 v130, v130, v240
	v_sub_f32_e32 v134, v134, v240
	v_exp_f32_e32 v202, v130
	v_sub_f32_e32 v130, v131, v240
	v_sub_f32_e32 v126, v126, v240
	v_sub_f32_e32 v122, v122, v240
	v_exp_f32_e32 v210, v134
	v_sub_f32_e32 v134, v135, v240
	v_exp_f32_e32 v200, v130
	v_sub_f32_e32 v130, v132, v240
	v_exp_f32_e32 v194, v126
	v_sub_f32_e32 v126, v127, v240
	v_exp_f32_e32 v140, v122
	v_sub_f32_e32 v122, v123, v240
	v_sub_f32_e32 v142, v188, v240
	v_exp_f32_e32 v208, v134
	v_sub_f32_e32 v134, v136, v240
	v_exp_f32_e32 v198, v130
	v_sub_f32_e32 v130, v133, v240
	v_exp_f32_e32 v192, v126
	v_sub_f32_e32 v126, v128, v240
	v_exp_f32_e32 v138, v122
	v_sub_f32_e32 v122, v124, v240
	v_exp_f32_e32 v206, v134
	v_sub_f32_e32 v134, v137, v240
	v_exp_f32_e32 v196, v130
	v_exp_f32_e32 v190, v126
	v_sub_f32_e32 v126, v129, v240
	v_exp_f32_e32 v130, v142
	v_exp_f32_e32 v188, v122
	v_sub_f32_e32 v122, v125, v240
	v_exp_f32_e32 v204, v134
	v_exp_f32_e32 v144, v126
	v_exp_f32_e32 v142, v122
	v_pk_mul_f32 v[112:113], v[112:113], v[0:1] op_sel_hi:[1,0]
	v_pk_mul_f32 v[110:111], v[110:111], v[0:1] op_sel_hi:[1,0]
	v_pk_mul_f32 v[108:109], v[108:109], v[0:1] op_sel_hi:[1,0]
	v_pk_mul_f32 v[106:107], v[106:107], v[0:1] op_sel_hi:[1,0]
	v_pk_mul_f32 v[104:105], v[104:105], v[0:1] op_sel_hi:[1,0]
	v_pk_mul_f32 v[102:103], v[102:103], v[0:1] op_sel_hi:[1,0]
	v_pk_mul_f32 v[100:101], v[100:101], v[0:1] op_sel_hi:[1,0]
	v_pk_mul_f32 v[98:99], v[98:99], v[0:1] op_sel_hi:[1,0]
	v_pk_mul_f32 v[92:93], v[92:93], v[0:1] op_sel_hi:[1,0]
	v_pk_mul_f32 v[90:91], v[90:91], v[0:1] op_sel_hi:[1,0]
	v_pk_mul_f32 v[72:73], v[72:73], v[0:1] op_sel_hi:[1,0]
	v_pk_mul_f32 v[70:71], v[70:71], v[0:1] op_sel_hi:[1,0]
	v_pk_mul_f32 v[40:41], v[40:41], v[0:1] op_sel_hi:[1,0]
	v_pk_mul_f32 v[38:39], v[38:39], v[0:1] op_sel_hi:[1,0]
	v_pk_mul_f32 v[36:37], v[36:37], v[0:1] op_sel_hi:[1,0]
	v_pk_mul_f32 v[34:35], v[34:35], v[0:1] op_sel_hi:[1,0]
	v_pk_mul_f32 v[32:33], v[32:33], v[130:131] op_sel_hi:[1,0]
	v_pk_mul_f32 v[30:31], v[30:31], v[130:131] op_sel_hi:[1,0]
	v_pk_mul_f32 v[28:29], v[28:29], v[130:131] op_sel_hi:[1,0]
	v_pk_mul_f32 v[26:27], v[26:27], v[130:131] op_sel_hi:[1,0]
	v_pk_mul_f32 v[24:25], v[24:25], v[130:131] op_sel_hi:[1,0]
	v_pk_mul_f32 v[22:23], v[22:23], v[130:131] op_sel_hi:[1,0]
	v_pk_mul_f32 v[20:21], v[20:21], v[130:131] op_sel_hi:[1,0]
	v_pk_mul_f32 v[18:19], v[18:19], v[130:131] op_sel_hi:[1,0]
	v_pk_mul_f32 v[16:17], v[16:17], v[130:131] op_sel_hi:[1,0]
	v_pk_mul_f32 v[14:15], v[14:15], v[130:131] op_sel_hi:[1,0]
	v_pk_mul_f32 v[12:13], v[12:13], v[130:131] op_sel_hi:[1,0]
	v_pk_mul_f32 v[10:11], v[10:11], v[130:131] op_sel_hi:[1,0]
	v_pk_mul_f32 v[8:9], v[8:9], v[130:131] op_sel_hi:[1,0]
	v_pk_mul_f32 v[6:7], v[6:7], v[130:131] op_sel_hi:[1,0]
	v_pk_mul_f32 v[4:5], v[4:5], v[130:131] op_sel_hi:[1,0]
	v_pk_mul_f32 v[2:3], v[2:3], v[130:131] op_sel_hi:[1,0]
	v_cvt_pk_bf16_f32 v116, v203, v201
	v_cvt_pk_bf16_f32 v117, v199, v197
	v_cvt_pk_bf16_f32 v118, v195, v193
	v_cvt_pk_bf16_f32 v119, v191, v145
	v_cvt_pk_bf16_f32 v120, v141, v139
	v_cvt_pk_bf16_f32 v121, v189, v143
	v_cvt_pk_bf16_f32 v122, v210, v208
	v_cvt_pk_bf16_f32 v123, v206, v204
	v_cvt_pk_bf16_f32 v124, v202, v200
	v_cvt_pk_bf16_f32 v125, v198, v196
	v_cvt_pk_bf16_f32 v126, v194, v192
	v_cvt_pk_bf16_f32 v127, v190, v144
	v_cvt_pk_bf16_f32 v128, v140, v138
	v_cvt_pk_bf16_f32 v129, v188, v142
	s_cbranch_vccnz .LBB0_727
	v_add_u32_e32 v131, s54, v160
	ds_read_b128 v[132:135], v131 offset:49152
	ds_read_b128 v[220:223], v131 offset:50176
	ds_read_b128 v[242:245], v131 offset:51200
	ds_read_b128 v[246:249], v131 offset:52224
	s_waitcnt lgkmcnt(3)
	v_mfma_f32_16x16x32_bf16 v[110:113], v[132:135], v[114:117], v[110:113]
	v_mfma_f32_16x16x32_bf16 v[30:33], v[132:135], v[122:125], v[30:33]
	s_waitcnt lgkmcnt(2)
	v_mfma_f32_16x16x32_bf16 v[110:113], v[220:223], v[118:121], v[110:113]
	v_mfma_f32_16x16x32_bf16 v[30:33], v[220:223], v[126:129], v[30:33]
	ds_read_b128 v[132:135], v131 offset:53248
	ds_read_b128 v[220:223], v131 offset:54272
	s_waitcnt lgkmcnt(2)
	v_mfma_f32_16x16x32_bf16 v[106:109], v[242:245], v[114:117], v[106:109]
	v_mfma_f32_16x16x32_bf16 v[26:29], v[242:245], v[122:125], v[26:29]
	v_mfma_f32_16x16x32_bf16 v[106:109], v[246:249], v[118:121], v[106:109]
	v_mfma_f32_16x16x32_bf16 v[26:29], v[246:249], v[126:129], v[26:29]
	ds_read_b128 v[242:245], v131 offset:55296
	ds_read_b128 v[246:249], v131 offset:56320
	s_waitcnt lgkmcnt(2)
	v_mfma_f32_16x16x32_bf16 v[102:105], v[132:135], v[114:117], v[102:105]
	v_mfma_f32_16x16x32_bf16 v[22:25], v[132:135], v[122:125], v[22:25]
	v_mfma_f32_16x16x32_bf16 v[102:105], v[220:223], v[118:121], v[102:105]
	v_mfma_f32_16x16x32_bf16 v[22:25], v[220:223], v[126:129], v[22:25]
	ds_read_b128 v[132:135], v131 offset:57344
	ds_read_b128 v[220:223], v131 offset:58368
	s_waitcnt lgkmcnt(2)
	v_mfma_f32_16x16x32_bf16 v[98:101], v[242:245], v[114:117], v[98:101]
	v_mfma_f32_16x16x32_bf16 v[18:21], v[242:245], v[122:125], v[18:21]
	v_mfma_f32_16x16x32_bf16 v[98:101], v[246:249], v[118:121], v[98:101]
	v_mfma_f32_16x16x32_bf16 v[18:21], v[246:249], v[126:129], v[18:21]
	ds_read_b128 v[242:245], v131 offset:59392
	ds_read_b128 v[246:249], v131 offset:60416
	s_waitcnt lgkmcnt(2)
	v_mfma_f32_16x16x32_bf16 v[90:93], v[132:135], v[114:117], v[90:93]
	v_mfma_f32_16x16x32_bf16 v[14:17], v[132:135], v[122:125], v[14:17]
	v_mfma_f32_16x16x32_bf16 v[90:93], v[220:223], v[118:121], v[90:93]
	v_mfma_f32_16x16x32_bf16 v[14:17], v[220:223], v[126:129], v[14:17]
	ds_read_b128 v[132:135], v131 offset:61440
	ds_read_b128 v[220:223], v131 offset:62464
	s_waitcnt lgkmcnt(2)
	v_mfma_f32_16x16x32_bf16 v[70:73], v[242:245], v[114:117], v[70:73]
	v_mfma_f32_16x16x32_bf16 v[10:13], v[242:245], v[122:125], v[10:13]
	v_mfma_f32_16x16x32_bf16 v[70:73], v[246:249], v[118:121], v[70:73]
	v_mfma_f32_16x16x32_bf16 v[10:13], v[246:249], v[126:129], v[10:13]
	ds_read_b128 v[242:245], v131 offset:63488
	ds_read_b128 v[246:249], v131 offset:64512
	s_waitcnt lgkmcnt(2)
	v_mfma_f32_16x16x32_bf16 v[38:41], v[132:135], v[114:117], v[38:41]
	v_mfma_f32_16x16x32_bf16 v[6:9], v[132:135], v[122:125], v[6:9]
	v_mfma_f32_16x16x32_bf16 v[38:41], v[220:223], v[118:121], v[38:41]
	v_mfma_f32_16x16x32_bf16 v[6:9], v[220:223], v[126:129], v[6:9]
	s_waitcnt lgkmcnt(0)
	v_mfma_f32_16x16x32_bf16 v[34:37], v[242:245], v[114:117], v[34:37]
	v_mfma_f32_16x16x32_bf16 v[2:5], v[242:245], v[122:125], v[2:5]
	v_mfma_f32_16x16x32_bf16 v[34:37], v[246:249], v[118:121], v[34:37]
	v_mfma_f32_16x16x32_bf16 v[2:5], v[246:249], v[126:129], v[2:5]
	s_mov_b64 s[4:5], 0
	s_branch .LBB0_728
